# adds: grid-barrier buffer_inv issued right after arrival (hidden under the wait); fused-norm exchange reads partial sums with sc1 loads instead of acquire fence
# speedup vs baseline: 1.0167x; 1.0081x over previous
; __device__ __forceinline__ unsigned xb_ld(unsigned* p)              { return __hip_atomic_load(p, __ATOMIC_RELAXED, __HIP_MEMORY_SCOPE_AGENT); }
; #define XB_SPIN(cond, bar) do { unsigned _sp = 0; while (cond) { __builtin_amdgcn_s_sleep(1); \
;     if ((++_sp & 255u) == 0u) { if (xb_ld(&(bar)[XB_TMO])) break; if (_sp > XB_SPIN_CAP) { atomicAdd(&(bar)[XB_TMO], 1u); break; } } } } while (0)
; __device__ __forceinline__ void xcd_barrier(const XcdBarrier& b) {
;     ...
;     if (threadIdx.x == 0) {
;         unsigned* bar = b.bar;
;         __builtin_amdgcn_s_waitcnt(0);
;         unsigned nloc = b.st[0], nx = b.st[1];
;         if (nloc == 0u) { xcd_barrier_complete(bar, b.x, nloc, nx); b.st[0] = nloc; b.st[1] = nx; }
;         const unsigned k1 = b.st[2] + 1u, rank = b.st[3]; b.st[2] = k1;
;         (void)__hip_atomic_fetch_add(&bar[XB_XSUB(b.x)], 1u, __ATOMIC_RELAXED, __HIP_MEMORY_SCOPE_AGENT);
;         if (rank == 0u) {
;             XB_SPIN(xb_ld(&bar[XB_XSUB(b.x)]) < k1 * nloc, bar);
.LBB0_92:
	v_mov_b32_e32 v4, s93
	ds_read_b32 v2, v4 offset:8
	s_lshl_b32 s3, s2, 8
	s_add_u32 s3, s30, s3
	ds_read_b32 v6, v4 offset:12
	s_addc_u32 s4, s31, 0
	s_waitcnt lgkmcnt(0)
	v_add_u32_e32 v2, 1, v2
	ds_write_b32 v4, v2 offset:8
	v_mov_b32_e32 v4, s3
	v_add_co_u32_e32 v4, vcc, 0x1000, v4
	v_mov_b32_e32 v5, s4
	s_nop 0
	v_addc_co_u32_e32 v5, vcc, 0, v5, vcc
	v_mov_b32_e32 v7, 1
	flat_atomic_add v[4:5], v7 offset:1024
	buffer_inv sc1
	s_add_u32 s6, s3, 0x1400
	v_cmp_ne_u32_e32 vcc, 0, v6
	s_addc_u32 s7, s4, 0
	s_cbranch_vccnz .LBB0_105
	v_mov_b64_e32 v[4:5], s[6:7]
	flat_load_dword v4, v[4:5] sc1
	v_mul_lo_u32 v3, v2, v3
	s_waitcnt vmcnt(0) lgkmcnt(0)
	v_cmp_lt_u32_e32 vcc, v4, v3
	s_and_saveexec_b64 s[4:5], vcc
	s_cbranch_execz .LBB0_104
	s_mov_b32 s3, 1
	s_mov_b64 s[8:9], 0
	s_branch .LBB0_96

; __device__ __forceinline__ unsigned xb_ld(unsigned* p)              { return __hip_atomic_load(p, __ATOMIC_RELAXED, __HIP_MEMORY_SCOPE_AGENT); }
; #define XB_SPIN(cond, bar) do { unsigned _sp = 0; while (cond) { __builtin_amdgcn_s_sleep(1); \
;     if ((++_sp & 255u) == 0u) { if (xb_ld(&(bar)[XB_TMO])) break; if (_sp > XB_SPIN_CAP) { atomicAdd(&(bar)[XB_TMO], 1u); break; } } } } while (0)
; __device__ __forceinline__ void xcd_barrier(const XcdBarrier& b) {
;     ...
;         XB_SPIN(xb_ld(&bar[XB_TOP]) < k1 * nx, bar);
;         __builtin_amdgcn_fence(__ATOMIC_ACQUIRE, "agent");
;         asm volatile("s_waitcnt vmcnt(0)" ::: "memory");
.LBB0_116:
	s_or_b64 exec, exec, s[4:5]
	s_waitcnt vmcnt(0) lgkmcnt(0)
	s_waitcnt vmcnt(0)

; __device__ __forceinline__ unsigned xb_ld(unsigned* p)              { return __hip_atomic_load(p, __ATOMIC_RELAXED, __HIP_MEMORY_SCOPE_AGENT); }
; #define XB_SPIN(cond, bar) do { unsigned _sp = 0; while (cond) { __builtin_amdgcn_s_sleep(1); \
;     if ((++_sp & 255u) == 0u) { if (xb_ld(&(bar)[XB_TMO])) break; if (_sp > XB_SPIN_CAP) { atomicAdd(&(bar)[XB_TMO], 1u); break; } } } } while (0)
; __device__ __forceinline__ void xcd_barrier(const XcdBarrier& b) {
;     ...
;         XB_SPIN(xb_ld(&bar[XB_TOP]) < k1 * nx, bar);
;         __builtin_amdgcn_fence(__ATOMIC_ACQUIRE, "agent");
;         asm volatile("s_waitcnt vmcnt(0)" ::: "memory");
.LBB0_121:
	s_or_b64 exec, exec, s[8:9]
	s_waitcnt vmcnt(0) lgkmcnt(0)
	s_waitcnt vmcnt(0)

; __device__ __forceinline__ unsigned xb_ld(unsigned* p)              { return __hip_atomic_load(p, __ATOMIC_RELAXED, __HIP_MEMORY_SCOPE_AGENT); }
; #define XB_SPIN(cond, bar) do { unsigned _sp = 0; while (cond) { __builtin_amdgcn_s_sleep(1); \
;     if ((++_sp & 255u) == 0u) { if (xb_ld(&(bar)[XB_TMO])) break; if (_sp > XB_SPIN_CAP) { atomicAdd(&(bar)[XB_TMO], 1u); break; } } } } while (0)
; __device__ __forceinline__ void xcd_barrier(const XcdBarrier& b) {
;     ...
;     if (threadIdx.x == 0) {
;         unsigned* bar = b.bar;
;         __builtin_amdgcn_s_waitcnt(0);
;         unsigned nloc = b.st[0], nx = b.st[1];
;         if (nloc == 0u) { xcd_barrier_complete(bar, b.x, nloc, nx); b.st[0] = nloc; b.st[1] = nx; }
;         const unsigned k1 = b.st[2] + 1u, rank = b.st[3]; b.st[2] = k1;
;         (void)__hip_atomic_fetch_add(&bar[XB_XSUB(b.x)], 1u, __ATOMIC_RELAXED, __HIP_MEMORY_SCOPE_AGENT);
;         if (rank == 0u) {
;             XB_SPIN(xb_ld(&bar[XB_XSUB(b.x)]) < k1 * nloc, bar);
.LBB0_235:
	v_mov_b32_e32 v6, s93
	ds_read_b32 v3, v6 offset:8
	v_readlane_b32 s12, v253, 40
	s_lshl_b32 s12, s12, 2
	s_add_u32 s12, s10, s12
	ds_read_b32 v8, v6 offset:12
	s_waitcnt lgkmcnt(0)
	v_add_u32_e32 v3, 1, v3
	s_addc_u32 s13, s11, 0
	ds_write_b32 v6, v3 offset:8
	v_mov_b32_e32 v6, s12
	v_add_co_u32_e32 v6, vcc, 0x1000, v6
	v_mov_b32_e32 v7, s13
	s_nop 0
	v_addc_co_u32_e32 v7, vcc, 0, v7, vcc
	flat_atomic_add v[6:7], v252 offset:1024
	buffer_inv sc1
	s_add_u32 s14, s12, 0x1400
	v_cmp_ne_u32_e32 vcc, 0, v8
	s_addc_u32 s15, s13, 0
	s_cbranch_vccnz .LBB0_248
	v_mov_b64_e32 v[6:7], s[14:15]
	flat_load_dword v6, v[6:7] sc1
	v_mul_lo_u32 v4, v3, v4
	s_waitcnt vmcnt(0) lgkmcnt(0)
	v_cmp_lt_u32_e32 vcc, v6, v4
	s_and_saveexec_b64 s[12:13], vcc
	s_cbranch_execz .LBB0_247
	s_mov_b32 s38, 1
	s_mov_b64 s[16:17], 0
	s_branch .LBB0_239

; __device__ __forceinline__ unsigned xb_ld(unsigned* p)              { return __hip_atomic_load(p, __ATOMIC_RELAXED, __HIP_MEMORY_SCOPE_AGENT); }
; #define XB_SPIN(cond, bar) do { unsigned _sp = 0; while (cond) { __builtin_amdgcn_s_sleep(1); \
;     if ((++_sp & 255u) == 0u) { if (xb_ld(&(bar)[XB_TMO])) break; if (_sp > XB_SPIN_CAP) { atomicAdd(&(bar)[XB_TMO], 1u); break; } } } } while (0)
; __device__ __forceinline__ void xcd_barrier(const XcdBarrier& b) {
;     ...
;         XB_SPIN(xb_ld(&bar[XB_TOP]) < k1 * nx, bar);
;         __builtin_amdgcn_fence(__ATOMIC_ACQUIRE, "agent");
;         asm volatile("s_waitcnt vmcnt(0)" ::: "memory");
.LBB0_259:
	s_or_b64 exec, exec, s[12:13]
	s_waitcnt vmcnt(0) lgkmcnt(0)
	s_waitcnt vmcnt(0)

;     __device__ __forceinline__ void fused(f32x4 (&acc)[2][2][4][2], const Unit& u, int wr, int wc, int fr, int fq, LAS unsigned char* lds, int wid, int lane) const {
;     ...
;             __builtin_amdgcn_fence(__ATOMIC_ACQUIRE, "agent");
;         }
;         asm volatile("s_waitcnt vmcnt(0) lgkmcnt(0)" ::: "memory"); __builtin_amdgcn_s_barrier(); asm volatile("" ::: "memory");
;         if (tid < 256) { const f32x4* sl = (const f32x4*)(xbuf + (size_t)(u.pm * BM + tid) * 8);
;             const f32x4 a = sl[0], b = sl[1]; const float t = ((a.x + a.y) + (a.z + a.w)) + ((b.x + b.y) + (b.z + b.w));
;             S[tid] = alpha * __builtin_amdgcn_rsqf(t * (1.0f / 2048.0f) + 1e-6f); }
.LBB0_321:
	s_waitcnt vmcnt(0) lgkmcnt(0)
	s_barrier
	s_lshl_b32 s11, s46, 8
	s_and_saveexec_b64 s[20:21], s[42:43]
	s_cbranch_execz .LBB0_323
	v_add_u32_e32 v70, s11, v2
	v_ashrrev_i32_e32 v71, 31, v70
	v_lshlrev_b64 v[70:71], 5, v[70:71]
	v_lshl_add_u64 v[76:77], s[16:17], 0, v[70:71]
	global_load_dwordx4 v[70:73], v[76:77], off sc1
	s_nop 0
	global_load_dwordx4 v[76:79], v[76:77], off offset:16 sc1
	v_lshl_add_u32 v2, v2, 2, 0
	v_add_u32_e32 v2, 0x21400, v2
	s_waitcnt vmcnt(0)
	v_mov_b32_e32 v80, v70
	v_mov_b32_e32 v81, v76
	v_mov_b32_e32 v76, v71
	v_mov_b32_e32 v70, v72
	v_mov_b32_e32 v71, v78
	v_mov_b32_e32 v78, v73
	v_pk_add_f32 v[72:73], v[80:81], v[76:77]
	v_pk_add_f32 v[70:71], v[70:71], v[78:79]
	s_nop 0
	v_pk_add_f32 v[70:71], v[72:73], v[70:71]
	s_nop 0
	v_add_f32_e32 v4, v70, v71
	v_fmamk_f32 v4, v4, 0x3a000000, v1
	v_rsq_f32_e32 v4, v4
	s_nop 0
	v_mul_f32_e32 v4, 0.5, v4
	ds_write_b32 v2, v4

; __device__ __forceinline__ unsigned xb_ld(unsigned* p)              { return __hip_atomic_load(p, __ATOMIC_RELAXED, __HIP_MEMORY_SCOPE_AGENT); }
; #define XB_SPIN(cond, bar) do { unsigned _sp = 0; while (cond) { __builtin_amdgcn_s_sleep(1); \
;     if ((++_sp & 255u) == 0u) { if (xb_ld(&(bar)[XB_TMO])) break; if (_sp > XB_SPIN_CAP) { atomicAdd(&(bar)[XB_TMO], 1u); break; } } } } while (0)
; __device__ __forceinline__ void xcd_barrier(const XcdBarrier& b) {
;     ...
;     if (threadIdx.x == 0) {
;         unsigned* bar = b.bar;
;         __builtin_amdgcn_s_waitcnt(0);
;         unsigned nloc = b.st[0], nx = b.st[1];
;         if (nloc == 0u) { xcd_barrier_complete(bar, b.x, nloc, nx); b.st[0] = nloc; b.st[1] = nx; }
;         const unsigned k1 = b.st[2] + 1u, rank = b.st[3]; b.st[2] = k1;
;         (void)__hip_atomic_fetch_add(&bar[XB_XSUB(b.x)], 1u, __ATOMIC_RELAXED, __HIP_MEMORY_SCOPE_AGENT);
;         if (rank == 0u) {
;             XB_SPIN(xb_ld(&bar[XB_XSUB(b.x)]) < k1 * nloc, bar);
.LBB0_472:
	v_mov_b32_e32 v6, s93
	ds_read_b32 v3, v6 offset:8
	v_readlane_b32 s10, v253, 40
	s_lshl_b32 s10, s10, 2
	s_add_u32 s10, s8, s10
	ds_read_b32 v8, v6 offset:12
	s_waitcnt lgkmcnt(0)
	v_add_u32_e32 v3, 1, v3
	s_addc_u32 s11, s9, 0
	ds_write_b32 v6, v3 offset:8
	v_mov_b32_e32 v6, s10
	v_add_co_u32_e32 v6, vcc, 0x1000, v6
	v_mov_b32_e32 v7, s11
	s_nop 0
	v_addc_co_u32_e32 v7, vcc, 0, v7, vcc
	flat_atomic_add v[6:7], v252 offset:1024
	buffer_inv sc1
	s_add_u32 s12, s10, 0x1400
	v_cmp_ne_u32_e32 vcc, 0, v8
	s_addc_u32 s13, s11, 0
	s_cbranch_vccnz .LBB0_485
	v_mov_b64_e32 v[6:7], s[12:13]
	flat_load_dword v6, v[6:7] sc1
	v_mul_lo_u32 v4, v3, v4
	s_waitcnt vmcnt(0) lgkmcnt(0)
	v_cmp_lt_u32_e32 vcc, v6, v4
	s_and_saveexec_b64 s[10:11], vcc
	s_cbranch_execz .LBB0_484
	s_mov_b32 s28, 1
	s_mov_b64 s[14:15], 0
	s_branch .LBB0_476

; __device__ __forceinline__ unsigned xb_ld(unsigned* p)              { return __hip_atomic_load(p, __ATOMIC_RELAXED, __HIP_MEMORY_SCOPE_AGENT); }
; #define XB_SPIN(cond, bar) do { unsigned _sp = 0; while (cond) { __builtin_amdgcn_s_sleep(1); \
;     if ((++_sp & 255u) == 0u) { if (xb_ld(&(bar)[XB_TMO])) break; if (_sp > XB_SPIN_CAP) { atomicAdd(&(bar)[XB_TMO], 1u); break; } } } } while (0)
; __device__ __forceinline__ void xcd_barrier(const XcdBarrier& b) {
;     ...
;         XB_SPIN(xb_ld(&bar[XB_TOP]) < k1 * nx, bar);
;         __builtin_amdgcn_fence(__ATOMIC_ACQUIRE, "agent");
;         asm volatile("s_waitcnt vmcnt(0)" ::: "memory");
.LBB0_496:
	s_or_b64 exec, exec, s[10:11]
	s_waitcnt vmcnt(0) lgkmcnt(0)
	s_waitcnt vmcnt(0)

; __device__ __forceinline__ unsigned xb_ld(unsigned* p)              { return __hip_atomic_load(p, __ATOMIC_RELAXED, __HIP_MEMORY_SCOPE_AGENT); }
; #define XB_SPIN(cond, bar) do { unsigned _sp = 0; while (cond) { __builtin_amdgcn_s_sleep(1); \
;     if ((++_sp & 255u) == 0u) { if (xb_ld(&(bar)[XB_TMO])) break; if (_sp > XB_SPIN_CAP) { atomicAdd(&(bar)[XB_TMO], 1u); break; } } } } while (0)
; __device__ __forceinline__ void xcd_barrier(const XcdBarrier& b) {
;     ...
;     if (threadIdx.x == 0) {
;         unsigned* bar = b.bar;
;         __builtin_amdgcn_s_waitcnt(0);
;         unsigned nloc = b.st[0], nx = b.st[1];
;         if (nloc == 0u) { xcd_barrier_complete(bar, b.x, nloc, nx); b.st[0] = nloc; b.st[1] = nx; }
;         const unsigned k1 = b.st[2] + 1u, rank = b.st[3]; b.st[2] = k1;
;         (void)__hip_atomic_fetch_add(&bar[XB_XSUB(b.x)], 1u, __ATOMIC_RELAXED, __HIP_MEMORY_SCOPE_AGENT);
;         if (rank == 0u) {
;             XB_SPIN(xb_ld(&bar[XB_XSUB(b.x)]) < k1 * nloc, bar);
.LBB0_566:
	v_mov_b32_e32 v6, s93
	ds_read_b32 v3, v6 offset:8
	v_readlane_b32 s8, v253, 40
	s_lshl_b32 s8, s8, 2
	s_add_u32 s8, s6, s8
	ds_read_b32 v8, v6 offset:12
	s_waitcnt lgkmcnt(0)
	v_add_u32_e32 v3, 1, v3
	s_addc_u32 s9, s7, 0
	ds_write_b32 v6, v3 offset:8
	v_mov_b32_e32 v6, s8
	v_add_co_u32_e32 v6, vcc, 0x1000, v6
	v_mov_b32_e32 v7, s9
	s_nop 0
	v_addc_co_u32_e32 v7, vcc, 0, v7, vcc
	flat_atomic_add v[6:7], v252 offset:1024
	buffer_inv sc1
	s_add_u32 s10, s8, 0x1400
	v_cmp_ne_u32_e32 vcc, 0, v8
	s_addc_u32 s11, s9, 0
	s_cbranch_vccnz .LBB0_579
	v_mov_b64_e32 v[6:7], s[10:11]
	flat_load_dword v6, v[6:7] sc1
	v_mul_lo_u32 v4, v3, v4
	s_waitcnt vmcnt(0) lgkmcnt(0)
	v_cmp_lt_u32_e32 vcc, v6, v4
	s_and_saveexec_b64 s[8:9], vcc
	s_cbranch_execz .LBB0_578
	s_mov_b32 s26, 1
	s_mov_b64 s[12:13], 0
	s_branch .LBB0_570

;     __device__ __forceinline__ HT hload(unsigned eoff) const { const u32x2 a = *(const u32x2*)((const char*)hi + eoff * 2u); const u32x2 b = *(const u32x2*)((const char*)lo + eoff * 2u); return (u32x4){a.x, a.y, b.x, b.y}; }
;     __device__ __forceinline__ void fused(f32x4 (&acc)[2][2][4][2], const Unit& u, int wr, int wc, int fr, int fq, LAS unsigned char* lds, int wid, int lane) const {
;     ...
; #pragma unroll
;         for (int j = 0; j < 16; ++j) H[j] = hload(rbase + (unsigned)(j * D));
;         if (wid == 0) {
;             const unsigned long long t0 = __builtin_amdgcn_s_memrealtime();
;             for (;;) {
;                 if ((unsigned)__builtin_amdgcn_readfirstlane((int)__hip_atomic_load(cnt + 64 * u.pm, __ATOMIC_RELAXED, __HIP_MEMORY_SCOPE_AGENT)) >= 32u) break;
;                 if (__builtin_amdgcn_s_memrealtime() - t0 > 2000000ull) { if (lane == 0) __hip_atomic_store(tmo, 1u, __ATOMIC_RELAXED, __HIP_MEMORY_SCOPE_AGENT); break; }
;                 __builtin_amdgcn_s_sleep(2);
;             }
;             __builtin_amdgcn_fence(__ATOMIC_ACQUIRE, "agent");
;         }
;         asm volatile("s_waitcnt vmcnt(0) lgkmcnt(0)" ::: "memory"); __builtin_amdgcn_s_barrier(); asm volatile("" ::: "memory");
;         if (tid < 256) { const f32x4* sl = (const f32x4*)(xbuf + (size_t)(u.pm * BM + tid) * 8);
;             const f32x4 a = sl[0], b = sl[1]; const float t = ((a.x + a.y) + (a.z + a.w)) + ((b.x + b.y) + (b.z + b.w));
;             S[tid] = alpha * __builtin_amdgcn_rsqf(t * (1.0f / 2048.0f) + 1e-6f); }
.LBB0_1066:
	s_waitcnt vmcnt(0) lgkmcnt(0)
	s_barrier
	v_mov_b32_e32 v97, v5
	v_mov_b32_e32 v95, v5
	v_mov_b32_e32 v91, v5
	v_mov_b32_e32 v85, v5
	v_mov_b32_e32 v93, v5
	v_mov_b32_e32 v89, v5
	v_mov_b32_e32 v83, v5
	v_mov_b32_e32 v77, v5
	v_mov_b32_e32 v87, v5
	v_mov_b32_e32 v81, v5
	v_mov_b32_e32 v75, v5
	v_mov_b32_e32 v71, v5
	v_mov_b32_e32 v79, v5
	v_mov_b32_e32 v73, v5
	v_mov_b32_e32 v3, v5
	v_lshl_add_u64 v[214:215], s[12:13], 0, v[4:5]
	v_lshl_add_u64 v[212:213], s[12:13], 0, v[96:97]
	v_lshl_add_u64 v[196:197], s[12:13], 0, v[94:95]
	v_lshl_add_u64 v[192:193], s[12:13], 0, v[90:91]
	v_lshl_add_u64 v[184:185], s[12:13], 0, v[84:85]
	v_lshl_add_u64 v[182:183], s[12:13], 0, v[92:93]
	v_lshl_add_u64 v[180:181], s[12:13], 0, v[88:89]
	v_lshl_add_u64 v[178:179], s[12:13], 0, v[82:83]
	v_lshl_add_u64 v[168:169], s[12:13], 0, v[76:77]
	v_lshl_add_u64 v[166:167], s[12:13], 0, v[86:87]
	v_lshl_add_u64 v[164:165], s[12:13], 0, v[80:81]
	v_lshl_add_u64 v[162:163], s[12:13], 0, v[74:75]
	v_lshl_add_u64 v[152:153], s[12:13], 0, v[70:71]
	v_lshl_add_u64 v[150:151], s[12:13], 0, v[78:79]
	v_lshl_add_u64 v[148:149], s[12:13], 0, v[72:73]
	v_lshl_add_u64 v[146:147], s[12:13], 0, v[2:3]
	s_lshl_b32 s7, s53, 8
	s_and_saveexec_b64 s[16:17], s[42:43]
	s_cbranch_execz .LBB0_1068
	v_add_u32_e32 v2, s7, v134
	v_ashrrev_i32_e32 v3, 31, v2
	v_lshlrev_b64 v[2:3], 5, v[2:3]
	v_lshl_add_u64 v[2:3], s[14:15], 0, v[2:3]
	global_load_dwordx4 v[70:73], v[2:3], off sc1
	global_load_dwordx4 v[74:77], v[2:3], off offset:16 sc1
	s_waitcnt vmcnt(0)
	v_mov_b32_e32 v2, v70
	v_mov_b32_e32 v3, v74
	v_mov_b32_e32 v74, v71
	v_mov_b32_e32 v70, v72
	v_mov_b32_e32 v71, v76
	v_mov_b32_e32 v76, v73
	v_pk_add_f32 v[2:3], v[2:3], v[74:75]
	v_pk_add_f32 v[70:71], v[70:71], v[76:77]
	s_nop 0
	v_pk_add_f32 v[2:3], v[2:3], v[70:71]
	s_nop 0
	v_add_f32_e32 v2, v2, v3
	v_fmamk_f32 v2, v2, 0x3a000000, v1
	v_rsq_f32_e32 v2, v2
	v_lshl_add_u32 v3, v134, 2, 0
	v_add_u32_e32 v3, 0x21400, v3
	ds_write_b32 v3, v2
